# speedup vs baseline: 1.0320x; 1.0027x over previous
; #define LAS __attribute__((address_space(3)))
; #define GAS __attribute__((address_space(1)))
; __device__ __forceinline__ void attn_unit(LAS unsigned char* lds, bf16_t* Qm, const bf16_t* __restrict__ Kb, const bf16_t* __restrict__ Vt,
;                                           int b, int h, int qb, int lgS, float lam, float oscale, const float* __restrict__ subg, float* stash) {
;     ...
;         const bf16_t* qp = Qm + (size_t)(tok0 + r32) * MIXW + (2 * h + c) * 64 + hi * 8;
;         bf16x8 qf[4];
; #pragma unroll
;         for (int d0 = 0; d0 < 4; ++d0) qf[d0] = *(const GAS bf16x8*)(qp + d0 * 16);
; #pragma unroll
;         for (int i = 0; i < 4; ++i)
; #pragma unroll
;             for (int r = 0; r < 16; ++r) o[i][r] = 0.f;
;         float mhat, lrun;
;         f32x16 negm;
; #pragma unroll
;         for (int r = 0; r < 16; ++r) negm[r] = 0.f;
;         const bf16_t* kg = Kb + (size_t)((b << lgS) + (tid >> 3)) * 512 + (2 * h + c) * 64 + (tid & 7) * 8;
;         const bf16_t* vg0 = Vt + ((size_t)(b * 512 + h * 128 + (tid >> 3)) << lgS) + (tid & 7) * 8;
;         const bf16_t* vg1 = vg0 + ((size_t)64 << lgS);
;         u32x4 kreg, vreg0, vreg1;
;         {
;             kreg = *(const GAS u32x4*)kg; vreg0 = *(const GAS u32x4*)vg0; vreg1 = *(const GAS u32x4*)vg1;
;             const u32x4 k1 = *(const GAS u32x4*)(kg + (size_t)64 * 512), k2 = *(const GAS u32x4*)(kg + (size_t)2 * 64 * 512), v10 = *(const GAS u32x4*)(vg0 + 64), v11 = *(const GAS u32x4*)(vg1 + 64);
;             *(LAS u32x4*)(lds + kw) = kreg; *(LAS u32x4*)(lds + vw0) = vreg0; *(LAS u32x4*)(lds + vw1) = vreg1;
;             *(LAS u32x4*)(lds + KBUF + kw) = k1; *(LAS u32x4*)(lds + VBUF + vw0) = v10; *(LAS u32x4*)(lds + VBUF + vw1) = v11;
;             *(LAS u32x4*)(lds + 2 * KBUF + kw) = k2;
;             kreg = *(const GAS u32x4*)(kg + (size_t)3 * 64 * 512); vreg0 = *(const GAS u32x4*)(vg0 + 2 * 64); vreg1 = *(const GAS u32x4*)(vg1 + 2 * 64);
.LBB0_349:
	s_and_b64 vcc, exec, s[26:27]
	s_cbranch_vccz .Lmy_skip_pf
	s_mov_b32 m0, 0x18000
	s_lshl_b32 s100, s5, 1
	s_add_i32 s100, s100, 128
	s_mov_b32 s101, 0
	v_lshl_add_u64 v[84:85], v[226:227], 0, s[100:101]
	global_load_lds_dword v[84:85], off
	v_lshl_add_u64 v[86:87], v[228:229], 0, s[100:101]
	global_load_lds_dword v[86:87], off
	s_add_u32 s100, s100, 0x10000
	v_lshl_add_u64 v[88:89], v[228:229], 0, s[100:101]
	global_load_lds_dword v[88:89], off
	s_add_u32 s100, s100, 0x10000
	v_lshl_add_u64 v[90:91], v[228:229], 0, s[100:101]
	global_load_lds_dword v[90:91], off
	s_add_u32 s100, s100, 0x10000
	v_lshl_add_u64 v[92:93], v[228:229], 0, s[100:101]
	global_load_lds_dword v[92:93], off
